# attention: exhausted flag also checked before every dequeue atomic (waves that finish later skip their failing fetch)
# speedup vs baseline: 1.0565x; 1.0091x over previous
; __device__ __forceinline__ void phase_attn(const Ctx& C, const float* relb  , int layer) {
;     ...
;           for (;;) {
;               unsigned idx = 0;
;               if (lane == 0) idx = __hip_atomic_fetch_add(qb_, 1u, __ATOMIC_RELAXED, __HIP_MEMORY_SCOPE_AGENT);
;               idx = (unsigned)__builtin_amdgcn_readfirstlane((int)idx);
;               if (idx >= (unsigned)per_q) break;
.LBB0_265:
	v_mov_b32_e32 v226, s101
	ds_read_b32 v227, v226
	s_waitcnt lgkmcnt(0)
	v_readfirstlane_b32 s98, v227
	s_nop 0
	s_cmp_lg_u32 s98, 0
	s_cbranch_scc1 .LBB0_299
	v_mov_b32_e32 v0, 0
	s_and_saveexec_b64 s[12:13], s[36:37]
	s_cbranch_execz .LBB0_267
	s_waitcnt lgkmcnt(0)
	v_mov_b64_e32 v[0:1], s[20:21]
	flat_atomic_add v0, v[0:1], v216 sc0

; __device__ __forceinline__ void phase_attn(const Ctx& C, const float* relb  , int layer) {
;     ...
;           for (;;) {
;               unsigned idx = 0;
;               if (lane == 0) idx = __hip_atomic_fetch_add(qa_, 1u, __ATOMIC_RELAXED, __HIP_MEMORY_SCOPE_AGENT);
;               idx = (unsigned)__builtin_amdgcn_readfirstlane((int)idx);
;               if (idx >= (unsigned)per_q) break;
.LBB0_302:
	v_mov_b32_e32 v226, s101
	ds_read_b32 v227, v226 offset:32
	s_waitcnt lgkmcnt(0)
	v_readfirstlane_b32 s98, v227
	s_nop 0
	s_cmp_lg_u32 s98, 0
	s_cbranch_scc1 .LBB0_261
	v_mov_b32_e32 v0, 0
	s_and_saveexec_b64 s[12:13], s[36:37]
	s_cbranch_execz .LBB0_304
	s_waitcnt lgkmcnt(0)
	v_mov_b64_e32 v[0:1], s[20:21]
	flat_atomic_add v0, v[0:1], v216 sc0
